# norm0 and L7 (norm2 + peer table) output stores made agent-scope write-through (sc1) so the following grid barrier's L2 write-back has less to flush
# speedup vs baseline: 1.0030x; 1.0030x over previous
.LBB0_194:
	s_or_b64 exec, exec, s[0:1]
	v_lshl_add_u64 v[52:53], v[0:1], 0, v[12:13]
	v_lshrrev_b32_e32 v0, 12, v6
	s_movk_i32 s0, 0x1800
	v_mad_u32_u24 v0, v0, s0, s0
	v_cndmask_b32_e64 v6, v0, 0, vcc
	v_lshl_add_u64 v[0:1], v[6:7], 2, s[88:89]
	s_mov_b64 s[0:1], 0x1000
	v_lshl_add_u64 v[54:55], v[0:1], 0, s[0:1]
	v_lshlrev_b64 v[2:3], 11, v[4:5]
	v_lshl_add_u64 v[24:25], v[54:55], 0, v[12:13]
	v_lshl_add_u64 v[22:23], v[0:1], 0, v[12:13]
	v_lshl_add_u64 v[20:21], v[10:11], 0, v[2:3]
	global_load_dwordx4 v[36:39], v[52:53], off
	global_load_dwordx4 v[40:43], v[8:9], off
	s_nop 0
	global_load_dwordx4 v[24:27], v[24:25], off
	s_nop 0
	global_load_dwordx4 v[0:3], v[22:23], off
	global_load_dwordx4 v[44:47], v[52:53], off offset:1024
	v_lshl_add_u64 v[62:63], v[54:55], 0, v[18:19]
	s_mov_b32 s0, 0x800000
	v_add_u32_e32 v4, s8, v4
	s_waitcnt vmcnt(4)
	v_mov_b32_e32 v48, v37
	s_waitcnt vmcnt(2)
	v_pk_add_f32 v[56:57], v[26:27], 1.0 op_sel_hi:[1,0]
	v_mov_b32_e32 v26, v36
	s_waitcnt vmcnt(0)
	v_mov_b32_e32 v49, v45
	v_mov_b32_e32 v27, v44
	v_pk_mul_f32 v[48:49], v[48:49], v[48:49]
	v_pk_add_f32 v[58:59], v[24:25], 1.0 op_sel_hi:[1,0]
	v_pk_fma_f32 v[26:27], v[26:27], v[26:27], v[48:49]
	v_mov_b32_e32 v48, v38
	v_mov_b32_e32 v49, v46
	v_pk_fma_f32 v[26:27], v[48:49], v[48:49], v[26:27]
	v_mov_b32_e32 v48, v39
	v_mov_b32_e32 v49, v47
	v_lshl_add_u64 v[24:25], v[54:55], 0, v[14:15]
	v_pk_fma_f32 v[60:61], v[48:49], v[48:49], v[26:27]
	v_lshl_add_u64 v[26:27], v[54:55], 0, v[16:17]
	global_load_dwordx4 v[48:51], v[52:53], off offset:2048
	v_add_f32_e32 v5, v60, v61
	global_load_dwordx4 v[52:55], v[52:53], off offset:3072
	s_waitcnt vmcnt(1)
	v_mov_b32_e32 v66, v49
	v_mov_b32_e32 v64, v48
	s_waitcnt vmcnt(0)
	v_mov_b32_e32 v67, v53
	v_mov_b32_e32 v65, v52
	v_pk_mul_f32 v[66:67], v[66:67], v[66:67]
	s_nop 0
	v_pk_fma_f32 v[64:65], v[64:65], v[64:65], v[66:67]
	v_mov_b32_e32 v66, v50
	v_mov_b32_e32 v67, v54
	v_pk_fma_f32 v[64:65], v[66:67], v[66:67], v[64:65]
	v_mov_b32_e32 v66, v51
	v_mov_b32_e32 v67, v55
	v_pk_fma_f32 v[64:65], v[66:67], v[66:67], v[64:65]
	s_nop 0
	v_add_f32_e32 v5, v5, v64
	v_add_f32_e32 v5, v5, v65
	ds_bpermute_b32 v6, v29, v5
	s_waitcnt lgkmcnt(0)
	v_add_f32_e32 v5, v5, v6
	ds_bpermute_b32 v6, v30, v5
	s_waitcnt lgkmcnt(0)
	v_add_f32_e32 v5, v5, v6
	ds_bpermute_b32 v6, v31, v5
	s_waitcnt lgkmcnt(0)
	v_add_f32_e32 v5, v5, v6
	ds_bpermute_b32 v6, v32, v5
	s_waitcnt lgkmcnt(0)
	v_add_f32_e32 v5, v5, v6
	ds_bpermute_b32 v6, v33, v5
	s_waitcnt lgkmcnt(0)
	v_add_f32_e32 v5, v5, v6
	ds_bpermute_b32 v6, v34, v5
	s_waitcnt lgkmcnt(0)
	v_add_f32_e32 v5, v5, v6
	v_fmamk_f32 v5, v5, 0x3a800000, v35
	v_cmp_gt_f32_e32 vcc, s0, v5
	v_mul_f32_e32 v6, 0x4b800000, v5
	s_movk_i32 s0, 0x2fff
	v_cndmask_b32_e32 v5, v5, v6, vcc
	v_rsq_f32_e32 v5, v5
	s_nop 0
	v_mul_f32_e32 v6, 0x45800000, v5
	v_cndmask_b32_e32 v6, v5, v6, vcc
	v_pk_mul_f32 v[36:37], v[36:37], v[6:7] op_sel_hi:[1,0]
	v_pk_mul_f32 v[38:39], v[38:39], v[6:7] op_sel_hi:[1,0]
	v_pk_mul_f32 v[36:37], v[40:41], v[36:37]
	v_pk_mul_f32 v[38:39], v[42:43], v[38:39]
	v_pk_fma_f32 v[0:1], v[58:59], v[36:37], v[0:1]
	v_pk_fma_f32 v[2:3], v[56:57], v[38:39], v[2:3]
	v_bfe_u32 v37, v1, 16, 1
	v_bfe_u32 v5, v3, 16, 1
	v_bfe_u32 v36, v2, 16, 1
	v_bfe_u32 v38, v0, 16, 1
	v_add3_u32 v0, v0, v38, s9
	v_add3_u32 v37, v1, v37, s9
	v_add3_u32 v1, v2, v36, s9
	v_add3_u32 v2, v3, v5, s9
	v_perm_b32 v1, v2, v1, s10
	v_perm_b32 v0, v37, v0, s10
	global_store_dwordx2 v[20:21], v[0:1], off sc1
	global_load_dwordx4 v[0:3], v[8:9], off offset:1024
	s_nop 0
	global_load_dwordx4 v[36:39], v[24:25], off
	global_load_dwordx4 v[40:43], v[22:23], off offset:1024
	v_pk_mul_f32 v[24:25], v[46:47], v[6:7] op_sel_hi:[1,0]
	v_pk_mul_f32 v[44:45], v[44:45], v[6:7] op_sel_hi:[1,0]
	v_cmp_lt_i32_e32 vcc, s0, v4
	s_or_b64 s[6:7], vcc, s[6:7]
	s_waitcnt vmcnt(2)
	v_pk_mul_f32 v[0:1], v[44:45], v[0:1]
	v_pk_mul_f32 v[2:3], v[24:25], v[2:3]
	s_waitcnt vmcnt(1)
	v_pk_add_f32 v[24:25], v[38:39], 1.0 op_sel_hi:[1,0]
	v_pk_add_f32 v[36:37], v[36:37], 1.0 op_sel_hi:[1,0]
	s_waitcnt vmcnt(0)
	v_pk_fma_f32 v[2:3], v[2:3], v[24:25], v[42:43]
	v_pk_fma_f32 v[0:1], v[0:1], v[36:37], v[40:41]
	v_bfe_u32 v25, v3, 16, 1
	v_bfe_u32 v5, v1, 16, 1
	v_bfe_u32 v24, v0, 16, 1
	v_bfe_u32 v36, v2, 16, 1
	v_add3_u32 v2, v2, v36, s9
	v_add3_u32 v3, v3, v25, s9
	v_add3_u32 v0, v0, v24, s9
	v_add3_u32 v1, v1, v5, s9
	v_perm_b32 v0, v1, v0, s10
	v_perm_b32 v1, v3, v2, s10
	global_store_dwordx2 v[20:21], v[0:1], off offset:512 sc1
	global_load_dwordx4 v[0:3], v[8:9], off offset:2048
	s_nop 0
	global_load_dwordx4 v[24:27], v[26:27], off
	s_nop 0
	global_load_dwordx4 v[36:39], v[22:23], off offset:2048
	v_pk_mul_f32 v[40:41], v[50:51], v[6:7] op_sel_hi:[1,0]
	v_pk_mul_f32 v[42:43], v[48:49], v[6:7] op_sel_hi:[1,0]
	s_waitcnt vmcnt(2)
	v_pk_mul_f32 v[2:3], v[40:41], v[2:3]
	v_pk_mul_f32 v[0:1], v[42:43], v[0:1]
	s_waitcnt vmcnt(1)
	v_pk_add_f32 v[26:27], v[26:27], 1.0 op_sel_hi:[1,0]
	v_pk_add_f32 v[24:25], v[24:25], 1.0 op_sel_hi:[1,0]
	s_waitcnt vmcnt(0)
	v_pk_fma_f32 v[2:3], v[2:3], v[26:27], v[38:39]
	v_pk_fma_f32 v[0:1], v[0:1], v[24:25], v[36:37]
	v_bfe_u32 v25, v3, 16, 1
	v_bfe_u32 v5, v1, 16, 1
	v_bfe_u32 v24, v0, 16, 1
	v_bfe_u32 v26, v2, 16, 1
	v_add3_u32 v2, v2, v26, s9
	v_add3_u32 v3, v3, v25, s9
	v_add3_u32 v0, v0, v24, s9
	v_add3_u32 v1, v1, v5, s9
	v_perm_b32 v0, v1, v0, s10
	v_perm_b32 v1, v3, v2, s10
	global_store_dwordx2 v[20:21], v[0:1], off offset:1024 sc1
	global_load_dwordx4 v[0:3], v[8:9], off offset:3072
	s_nop 0
	global_load_dwordx4 v[24:27], v[62:63], off
	global_load_dwordx4 v[36:39], v[22:23], off offset:3072
	v_pk_mul_f32 v[22:23], v[54:55], v[6:7] op_sel_hi:[1,0]
	v_pk_mul_f32 v[40:41], v[52:53], v[6:7] op_sel_hi:[1,0]
	s_waitcnt vmcnt(2)
	v_pk_mul_f32 v[2:3], v[22:23], v[2:3]
	v_pk_mul_f32 v[0:1], v[40:41], v[0:1]
	s_waitcnt vmcnt(1)
	v_pk_add_f32 v[22:23], v[26:27], 1.0 op_sel_hi:[1,0]
	v_pk_add_f32 v[24:25], v[24:25], 1.0 op_sel_hi:[1,0]
	s_waitcnt vmcnt(0)
	v_pk_fma_f32 v[2:3], v[2:3], v[22:23], v[38:39]
	v_pk_fma_f32 v[0:1], v[0:1], v[24:25], v[36:37]
	v_bfe_u32 v22, v3, 16, 1
	v_bfe_u32 v5, v1, 16, 1
	v_bfe_u32 v6, v0, 16, 1
	v_bfe_u32 v23, v2, 16, 1
	v_add3_u32 v2, v2, v23, s9
	v_add3_u32 v3, v3, v22, s9
	v_add3_u32 v0, v0, v6, s9
	v_add3_u32 v1, v1, v5, s9
	v_perm_b32 v0, v1, v0, s10
	v_perm_b32 v1, v3, v2, s10
	global_store_dwordx2 v[20:21], v[0:1], off offset:1536 sc1
	s_andn2_b64 exec, exec, s[6:7]
	s_cbranch_execz .LBB0_199

.LBB0_1189:
	v_ashrrev_i32_e32 v21, 31, v20
	v_lshlrev_b64 v[0:1], 12, v[20:21]
	v_lshl_add_u64 v[16:17], v[24:25], 0, v[0:1]
	v_add_u32_e32 v0, 0xfffff000, v20
	v_lshrrev_b32_e32 v0, 12, v0
	v_mad_u32_u24 v0, v0, s35, s35
	v_cmp_lt_i32_e32 vcc, s30, v20
	v_mov_b32_e32 v29, v149
	v_lshlrev_b64 v[2:3], 11, v[20:21]
	v_cndmask_b32_e32 v148, 0, v0, vcc
	v_lshl_add_u64 v[0:1], v[148:149], 2, s[4:5]
	v_lshl_add_u64 v[18:19], v[0:1], 0, s[8:9]
	v_lshl_add_u64 v[12:13], v[18:19], 0, v[28:29]
	v_lshl_add_u64 v[38:39], v[0:1], 0, v[28:29]
	v_lshl_add_u64 v[36:37], v[26:27], 0, v[2:3]
	global_load_dwordx4 v[8:11], v[16:17], off
	global_load_dwordx4 v[4:7], v[22:23], off
	s_nop 0
	global_load_dwordx4 v[12:15], v[12:13], off
	s_nop 0
	global_load_dwordx4 v[0:3], v[38:39], off
	v_mov_b32_e32 v31, v149
	v_mov_b32_e32 v33, v149
	v_mov_b32_e32 v35, v149
	v_lshl_add_u64 v[40:41], v[18:19], 0, v[30:31]
	v_add_u32_e32 v20, s23, v20
	global_load_dwordx4 v[56:59], v[16:17], off offset:2048
	s_waitcnt vmcnt(4)
	v_mov_b32_e32 v48, v9
	v_mov_b32_e32 v42, v8
	s_waitcnt vmcnt(2)
	v_pk_add_f32 v[44:45], v[14:15], 1.0 op_sel_hi:[1,0]
	v_pk_add_f32 v[46:47], v[12:13], 1.0 op_sel_hi:[1,0]
	global_load_dwordx4 v[12:15], v[16:17], off offset:1024
	s_waitcnt vmcnt(1)
	v_mov_b32_e32 v64, v57
	v_mov_b32_e32 v62, v56
	s_waitcnt vmcnt(0)
	v_mov_b32_e32 v49, v13
	v_mov_b32_e32 v43, v12
	v_pk_mul_f32 v[48:49], v[48:49], v[48:49]
	s_nop 0
	v_pk_fma_f32 v[42:43], v[42:43], v[42:43], v[48:49]
	v_mov_b32_e32 v48, v10
	v_mov_b32_e32 v49, v14
	v_pk_fma_f32 v[42:43], v[48:49], v[48:49], v[42:43]
	v_mov_b32_e32 v48, v11
	v_mov_b32_e32 v49, v15
	v_pk_fma_f32 v[60:61], v[48:49], v[48:49], v[42:43]
	v_lshl_add_u64 v[42:43], v[18:19], 0, v[32:33]
	v_lshl_add_u64 v[48:49], v[18:19], 0, v[34:35]
	global_load_dwordx4 v[16:19], v[16:17], off offset:3072
	v_add_f32_e32 v21, v60, v61
	s_waitcnt vmcnt(0)
	v_mov_b32_e32 v65, v17
	v_mov_b32_e32 v63, v16
	v_pk_mul_f32 v[64:65], v[64:65], v[64:65]
	s_nop 0
	v_pk_fma_f32 v[62:63], v[62:63], v[62:63], v[64:65]
	v_mov_b32_e32 v64, v58
	v_mov_b32_e32 v65, v18
	v_pk_fma_f32 v[62:63], v[64:65], v[64:65], v[62:63]
	v_mov_b32_e32 v64, v59
	v_mov_b32_e32 v65, v19
	v_pk_fma_f32 v[62:63], v[64:65], v[64:65], v[62:63]
	s_nop 0
	v_add_f32_e32 v21, v21, v62
	v_add_f32_e32 v21, v21, v63
	ds_bpermute_b32 v29, v50, v21
	s_waitcnt lgkmcnt(0)
	v_add_f32_e32 v21, v21, v29
	ds_bpermute_b32 v29, v51, v21
	s_waitcnt lgkmcnt(0)
	v_add_f32_e32 v21, v21, v29
	ds_bpermute_b32 v29, v52, v21
	s_waitcnt lgkmcnt(0)
	v_add_f32_e32 v21, v21, v29
	ds_bpermute_b32 v29, v53, v21
	s_waitcnt lgkmcnt(0)
	v_add_f32_e32 v21, v21, v29
	ds_bpermute_b32 v29, v54, v21
	s_waitcnt lgkmcnt(0)
	v_add_f32_e32 v21, v21, v29
	ds_bpermute_b32 v29, v55, v21
	s_waitcnt lgkmcnt(0)
	v_add_f32_e32 v21, v21, v29
	v_fmamk_f32 v21, v21, 0x3a800000, v185
	v_cmp_gt_f32_e32 vcc, s31, v21
	v_mul_f32_e32 v29, 0x4b800000, v21
	s_nop 0
	v_cndmask_b32_e32 v21, v21, v29, vcc
	v_rsq_f32_e32 v21, v21
	s_nop 0
	v_mul_f32_e32 v29, 0x45800000, v21
	v_cndmask_b32_e32 v60, v21, v29, vcc
	v_pk_mul_f32 v[8:9], v[8:9], v[60:61] op_sel_hi:[1,0]
	v_pk_mul_f32 v[10:11], v[10:11], v[60:61] op_sel_hi:[1,0]
	v_pk_mul_f32 v[4:5], v[4:5], v[8:9]
	v_pk_mul_f32 v[6:7], v[6:7], v[10:11]
	v_pk_fma_f32 v[0:1], v[46:47], v[4:5], v[0:1]
	v_pk_fma_f32 v[2:3], v[44:45], v[6:7], v[2:3]
	v_bfe_u32 v6, v1, 16, 1
	v_bfe_u32 v4, v3, 16, 1
	v_bfe_u32 v5, v2, 16, 1
	v_bfe_u32 v7, v0, 16, 1
	v_add3_u32 v0, v0, v7, s52
	v_add3_u32 v6, v1, v6, s52
	v_add3_u32 v1, v2, v5, s52
	v_add3_u32 v2, v3, v4, s52
	v_perm_b32 v1, v2, v1, s1
	v_perm_b32 v0, v6, v0, s1
	global_store_dwordx2 v[36:37], v[0:1], off sc1
	global_load_dwordx4 v[0:3], v[22:23], off offset:1024
	s_nop 0
	global_load_dwordx4 v[4:7], v[40:41], off
	global_load_dwordx4 v[8:11], v[38:39], off offset:1024
	v_pk_mul_f32 v[14:15], v[14:15], v[60:61] op_sel_hi:[1,0]
	v_pk_mul_f32 v[12:13], v[12:13], v[60:61] op_sel_hi:[1,0]
	v_cmp_lt_i32_e32 vcc, s36, v20
	s_or_b64 s[6:7], vcc, s[6:7]
	s_waitcnt vmcnt(2)
	v_pk_mul_f32 v[0:1], v[12:13], v[0:1]
	v_pk_mul_f32 v[2:3], v[14:15], v[2:3]
	s_waitcnt vmcnt(1)
	v_pk_add_f32 v[6:7], v[6:7], 1.0 op_sel_hi:[1,0]
	v_pk_add_f32 v[4:5], v[4:5], 1.0 op_sel_hi:[1,0]
	s_waitcnt vmcnt(0)
	v_pk_fma_f32 v[2:3], v[2:3], v[6:7], v[10:11]
	v_pk_fma_f32 v[0:1], v[0:1], v[4:5], v[8:9]
	v_bfe_u32 v6, v3, 16, 1
	v_bfe_u32 v4, v1, 16, 1
	v_bfe_u32 v5, v0, 16, 1
	v_bfe_u32 v7, v2, 16, 1
	v_add3_u32 v2, v2, v7, s52
	v_add3_u32 v3, v3, v6, s52
	v_add3_u32 v0, v0, v5, s52
	v_add3_u32 v1, v1, v4, s52
	v_perm_b32 v0, v1, v0, s1
	v_perm_b32 v1, v3, v2, s1
	global_store_dwordx2 v[36:37], v[0:1], off offset:512 sc1
	global_load_dwordx4 v[0:3], v[22:23], off offset:2048
	s_nop 0
	global_load_dwordx4 v[4:7], v[42:43], off
	global_load_dwordx4 v[8:11], v[38:39], off offset:2048
	v_pk_mul_f32 v[12:13], v[58:59], v[60:61] op_sel_hi:[1,0]
	v_pk_mul_f32 v[14:15], v[56:57], v[60:61] op_sel_hi:[1,0]
	s_waitcnt vmcnt(2)
	v_pk_mul_f32 v[2:3], v[12:13], v[2:3]
	v_pk_mul_f32 v[0:1], v[14:15], v[0:1]
	s_waitcnt vmcnt(1)
	v_pk_add_f32 v[6:7], v[6:7], 1.0 op_sel_hi:[1,0]
	v_pk_add_f32 v[4:5], v[4:5], 1.0 op_sel_hi:[1,0]
	s_waitcnt vmcnt(0)
	v_pk_fma_f32 v[2:3], v[2:3], v[6:7], v[10:11]
	v_pk_fma_f32 v[0:1], v[0:1], v[4:5], v[8:9]
	v_bfe_u32 v6, v3, 16, 1
	v_bfe_u32 v4, v1, 16, 1
	v_bfe_u32 v5, v0, 16, 1
	v_bfe_u32 v7, v2, 16, 1
	v_add3_u32 v2, v2, v7, s52
	v_add3_u32 v3, v3, v6, s52
	v_add3_u32 v0, v0, v5, s52
	v_add3_u32 v1, v1, v4, s52
	v_perm_b32 v0, v1, v0, s1
	v_perm_b32 v1, v3, v2, s1
	global_store_dwordx2 v[36:37], v[0:1], off offset:1024 sc1
	global_load_dwordx4 v[0:3], v[22:23], off offset:3072
	s_nop 0
	global_load_dwordx4 v[4:7], v[48:49], off
	global_load_dwordx4 v[8:11], v[38:39], off offset:3072
	v_pk_mul_f32 v[12:13], v[18:19], v[60:61] op_sel_hi:[1,0]
	v_pk_mul_f32 v[14:15], v[16:17], v[60:61] op_sel_hi:[1,0]
	s_waitcnt vmcnt(2)
	v_pk_mul_f32 v[2:3], v[12:13], v[2:3]
	v_pk_mul_f32 v[0:1], v[14:15], v[0:1]
	s_waitcnt vmcnt(1)
	v_pk_add_f32 v[6:7], v[6:7], 1.0 op_sel_hi:[1,0]
	v_pk_add_f32 v[4:5], v[4:5], 1.0 op_sel_hi:[1,0]
	s_waitcnt vmcnt(0)
	v_pk_fma_f32 v[2:3], v[2:3], v[6:7], v[10:11]
	v_pk_fma_f32 v[0:1], v[0:1], v[4:5], v[8:9]
	v_bfe_u32 v6, v3, 16, 1
	v_bfe_u32 v4, v1, 16, 1
	v_bfe_u32 v5, v0, 16, 1
	v_bfe_u32 v7, v2, 16, 1
	v_add3_u32 v2, v2, v7, s52
	v_add3_u32 v3, v3, v6, s52
	v_add3_u32 v0, v0, v5, s52
	v_add3_u32 v1, v1, v4, s52
	v_perm_b32 v0, v1, v0, s1
	v_perm_b32 v1, v3, v2, s1
	global_store_dwordx2 v[36:37], v[0:1], off offset:1536 sc1
	s_andn2_b64 exec, exec, s[6:7]
	s_cbranch_execnz .LBB0_1189

.LBB0_1193:
	s_movk_i32 s0, 0x4000
	v_cmp_gt_u32_e64 s[4:5], s0, v6
	v_mov_b32_e32 v3, s29
	v_mov_b32_e32 v4, s27
	v_cndmask_b32_e64 v5, v3, v4, s[4:5]
	v_mov_b32_e32 v3, s28
	v_mov_b32_e32 v4, s26
	v_and_b32_e32 v13, 0x3fff, v6
	v_cndmask_b32_e64 v4, v3, v4, s[4:5]
	v_lshl_add_u64 v[4:5], v[4:5], 0, s[8:9]
	v_lshlrev_b32_e32 v148, 12, v13
	v_lshl_add_u64 v[4:5], v[4:5], 0, v[148:149]
	v_mov_b32_e32 v3, v149
	v_lshl_add_u64 v[4:5], v[4:5], 0, v[2:3]
	global_load_dwordx4 v[14:17], v[4:5], off offset:48
	global_load_dwordx4 v[18:21], v[4:5], off offset:32
	global_load_dwordx4 v[22:25], v[4:5], off offset:16
	global_load_dwordx4 v[26:29], v[4:5], off
	v_cndmask_b32_e64 v148, v202, v203, s[4:5]
	s_waitcnt vmcnt(3)
	v_max_f32_e64 v32, |v16|, |v16|
	s_waitcnt vmcnt(2)
	v_max_f32_e64 v30, |v18|, |v18|
	s_waitcnt vmcnt(1)
	v_max_f32_e64 v5, |v24|, |v24|
	s_waitcnt vmcnt(0)
	v_max_f32_e64 v3, |v29|, |v29|
	v_max_f32_e64 v4, |v28|, |v28|
	v_max_f32_e32 v3, v4, v3
	v_max_f32_e64 v4, |v25|, |v25|
	v_max_f32_e32 v4, v5, v4
	v_max_f32_e64 v5, |v19|, |v19|
	v_max_f32_e32 v5, v30, v5
	v_max_f32_e64 v30, |v21|, |v21|
	v_max_f32_e64 v31, |v20|, |v20|
	v_max_f32_e32 v30, v31, v30
	v_max_f32_e64 v31, |v17|, |v17|
	v_max_f32_e32 v31, v32, v31
	v_max3_f32 v31, |v14|, |v15|, v31
	v_max3_f32 v3, |v26|, |v27|, v3
	v_max3_f32 v4, |v22|, |v23|, v4
	v_max3_f32 v5, v5, v30, v31
	v_max3_f32 v3, v3, v4, v5
	ds_bpermute_b32 v4, v7, v3
	s_waitcnt lgkmcnt(0)
	v_max_f32_e32 v4, v4, v4
	v_max_f32_e32 v3, v3, v4
	ds_bpermute_b32 v4, v8, v3
	s_waitcnt lgkmcnt(0)
	v_max_f32_e32 v4, v4, v4
	v_max_f32_e32 v3, v3, v4
	ds_bpermute_b32 v4, v9, v3
	s_waitcnt lgkmcnt(0)
	v_max_f32_e32 v4, v4, v4
	v_max_f32_e32 v3, v3, v4
	ds_bpermute_b32 v4, v10, v3
	s_waitcnt lgkmcnt(0)
	v_max_f32_e32 v4, v4, v4
	v_max_f32_e32 v3, v3, v4
	ds_bpermute_b32 v4, v11, v3
	s_waitcnt lgkmcnt(0)
	v_max_f32_e32 v4, v4, v4
	v_max_f32_e32 v3, v3, v4
	ds_bpermute_b32 v4, v12, v3
	s_waitcnt lgkmcnt(0)
	v_max_f32_e32 v4, v4, v4
	v_max_f32_e32 v3, v3, v4
	v_div_scale_f32 v4, s[12:13], v3, v3, s37
	v_rcp_f32_e32 v5, v4
	v_cmp_lt_f32_e64 s[0:1], 0, v3
	v_fma_f32 v30, -v4, v5, 1.0
	v_fmac_f32_e32 v5, v30, v5
	v_div_scale_f32 v30, vcc, s37, v3, s37
	v_mul_f32_e32 v31, v30, v5
	v_fma_f32 v32, -v4, v31, v30
	v_fmac_f32_e32 v31, v32, v5
	v_fma_f32 v4, -v4, v31, v30
	v_div_fmas_f32 v4, v4, v5, v31
	v_div_fixup_f32 v3, v4, v3, s37
	v_cndmask_b32_e64 v3, 1.0, v3, s[0:1]
	v_mul_f32_e32 v4, v26, v3
	v_mul_f32_e32 v5, v27, v3
	v_mov_b32_e32 v26, v149
	v_cvt_scalef32_pk_fp4_f32 v26, v4, v5, 1.0
	v_mul_f32_e32 v4, v28, v3
	v_mul_f32_e32 v5, v29, v3
	v_cvt_scalef32_pk_fp4_f32 v26, v4, v5, 1.0 op_sel:[0,0,1,0]
	v_mul_f32_e32 v4, v22, v3
	v_mul_f32_e32 v5, v23, v3
	v_cvt_scalef32_pk_fp4_f32 v26, v4, v5, 1.0 op_sel:[0,0,0,1]
	v_mul_f32_e32 v4, v24, v3
	v_mul_f32_e32 v5, v25, v3
	v_cvt_scalef32_pk_fp4_f32 v26, v4, v5, 1.0 op_sel:[0,0,1,1]
	v_mul_f32_e32 v4, v18, v3
	v_mul_f32_e32 v5, v19, v3
	v_mov_b32_e32 v27, v149
	v_cvt_scalef32_pk_fp4_f32 v27, v4, v5, 1.0
	v_mul_f32_e32 v4, v20, v3
	v_mul_f32_e32 v5, v21, v3
	v_cvt_scalef32_pk_fp4_f32 v27, v4, v5, 1.0 op_sel:[0,0,1,0]
	v_mul_f32_e32 v4, v14, v3
	v_mul_f32_e32 v5, v15, v3
	v_cvt_scalef32_pk_fp4_f32 v27, v4, v5, 1.0 op_sel:[0,0,0,1]
	v_mul_f32_e32 v4, v16, v3
	v_mul_f32_e32 v5, v17, v3
	v_cvt_scalef32_pk_fp4_f32 v27, v4, v5, 1.0 op_sel:[0,0,1,1]
	v_lshl_add_u64 v[4:5], s[82:83], 0, v[148:149]
	v_lshlrev_b32_e32 v148, 9, v13
	v_lshl_add_u64 v[14:15], v[4:5], 0, v[148:149]
	v_lshl_add_u64 v[14:15], v[14:15], 0, v[0:1]
	global_store_dwordx2 v[14:15], v[26:27], off sc1
	s_and_saveexec_b64 s[0:1], s[2:3]
	s_cbranch_execz .LBB0_1192
	v_div_scale_f32 v14, s[4:5], v3, v3, 1.0
	v_rcp_f32_e32 v15, v14
	v_div_scale_f32 v16, vcc, 1.0, v3, 1.0
	v_lshlrev_b32_e32 v148, 2, v13
	v_fma_f32 v17, -v14, v15, 1.0
	v_fmac_f32_e32 v15, v17, v15
	v_mul_f32_e32 v17, v16, v15
	v_fma_f32 v18, -v14, v17, v16
	v_fmac_f32_e32 v17, v18, v15
	v_fma_f32 v14, -v14, v17, v16
	v_lshl_add_u64 v[4:5], v[4:5], 0, v[148:149]
	v_div_fmas_f32 v14, v14, v15, v17
	v_add_co_u32_e32 v4, vcc, 0x1000000, v4
	v_div_fixup_f32 v3, v14, v3, 1.0
	s_nop 0
	v_addc_co_u32_e32 v5, vcc, 0, v5, vcc
	global_store_dword v[4:5], v3, off sc1
	s_branch .LBB0_1192
